# GEMM mainloop: s_setprio 1 moved before the barrier opening each MFMA segment and s_setprio 0 after the barrier closing it (two issue slots off each segment's critical path)
# speedup vs baseline: 1.0053x; 1.0053x over previous
; #define PG8_STAGE(bufoff, gbase, voff) do { _Pragma("unroll") for (int _i = 0; _i < 2; ++_i) \
;         __builtin_amdgcn_global_load_lds((const unsigned*)((const char*)(gbase) + (voff)[_i]), (LAS unsigned*)(lds + (bufoff) + ldsw + _i * 8192), 16, 0, 0); } while (0)
; #define PG8_LDA(dst, b, h) do { _Pragma("unroll") for (int m = 0; m < 4; ++m) _Pragma("unroll") for (int k = 0; k < 2; ++k) dst[m][k] = *(const LAS bf16x8*)(lds + PG8_SA(b, h) + aoff + m * 2048 + k * 1024); } while (0)
; #define PG8_WAIT_V(n) asm volatile("s_waitcnt vmcnt(" #n ")" ::: "memory")
; #define PG8_WAIT_L(n) asm volatile("s_waitcnt lgkmcnt(" #n ")" ::: "memory")
; template <class Epi>
; DI void gemm_phase(LAS unsigned char* lds, const Gemm g, const StaticOrder& S, const Epi& E, const int tid) {
;     ...
;         for (int t = 0; t < nt; t += 2) {
;             const bool last = (t == nt - 2);
;             const char* a1 = cA + (size_t)(t + 1) * kstep;
;             const char* a2 = last ? nA : cA + (size_t)(t + 2) * kstep; const char* b2 = last ? nB : cB + (size_t)(t + 2) * kstep;
;             const char* a3 = a2 + kstep; const char* b3 = b2 + kstep;
;             PG8_LDB(B0, 0, 0); PG8_SCHED; PG8_LDA(At, 0, 0); PG8_STAGE(PG8_SA(1, 1), a1 + hstep, voffA);
;             PG8_WAIT_L(8); PG8_BAR; PG8_WAIT_L(0); PG8_MMA(0, 0, At, B0); PG8_BAR; PG8_SCHED;
;             PG8_LDB(B1, 0, 1); PG8_STAGE(PG8_SB(0, 0), b2, voffB);
;             PG8_BAR; PG8_WAIT_L(0); PG8_MMA(0, 1, At, B1); PG8_BAR;
;             PG8_LDA(At, 0, 1); PG8_STAGE(PG8_SA(0, 0), a2, voffA);
;             PG8_BAR; PG8_WAIT_L(0); PG8_MMA(1, 0, At, B0); PG8_BAR; PG8_SCHED;
;             PG8_STAGE(PG8_SB(0, 1), b2 + hstep, voffB);
;             PG8_WAIT_V(6); PG8_BAR; PG8_MMA(1, 1, At, B1); PG8_BAR;
;             PG8_LDB(B0, 1, 0); PG8_SCHED; PG8_LDA(At, 1, 0); PG8_STAGE(PG8_SA(0, 1), a2 + hstep, voffA);
;             PG8_WAIT_L(8); PG8_BAR; PG8_WAIT_L(0); PG8_MMA(0, 0, At, B0); PG8_BAR; PG8_SCHED;
;             PG8_LDB(B1, 1, 1); PG8_STAGE(PG8_SB(1, 0), b3, voffB);
;             PG8_BAR; PG8_WAIT_L(0); PG8_MMA(0, 1, At, B1); PG8_BAR;
;             PG8_LDA(At, 1, 1); PG8_STAGE(PG8_SA(1, 0), a3, voffA);
;             PG8_BAR; PG8_WAIT_L(0); PG8_MMA(1, 0, At, B0); PG8_BAR; PG8_SCHED;
;             PG8_STAGE(PG8_SB(1, 1), b3 + hstep, voffB);
;             PG8_WAIT_V(6); PG8_BAR; PG8_MMA(1, 1, At, B1); PG8_BAR;
.LBB0_742:
	s_add_u32 s20, s20, 0x80
	s_addc_u32 s21, s21, 0
	s_add_u32 s81, s18, 0x100
	s_addc_u32 s82, s19, 0
	s_mov_b32 s18, 0
	ds_read_b128 v[138:141], v212
	ds_read_b128 v[150:153], v212 offset:1024
	ds_read_b128 v[154:157], v212 offset:2048
	ds_read_b128 v[158:161], v212 offset:3072
	s_add_i32 s83, s18, 2
	s_add_u32 s22, s20, 0x80
	s_addc_u32 s19, s21, 0
	s_cmp_eq_u32 s60, s18
	s_cselect_b32 s18, s8, s22
	s_cselect_b32 s19, s9, s19
	s_cselect_b32 s23, s17, s82
	s_cselect_b32 s22, s16, s81
	s_add_i32 m0, s49, 0xc000
	ds_read_b128 v[162:165], v148
	ds_read_b128 v[166:169], v148 offset:1024
	ds_read_b128 v[170:173], v148 offset:2048
	ds_read_b128 v[174:177], v148 offset:3072
	ds_read_b128 v[178:181], v148 offset:4096
	ds_read_b128 v[182:185], v148 offset:5120
	ds_read_b128 v[186:189], v148 offset:6144
	ds_read_b128 v[190:193], v148 offset:7168
	global_load_lds_dwordx4 v134, s[20:21]
	s_add_i32 m0, s49, 0xe000
	s_nop 0
	global_load_lds_dwordx4 v136, s[20:21]
	s_waitcnt lgkmcnt(8)
	s_setprio 1
	s_barrier
	s_waitcnt lgkmcnt(0)
	v_mfma_f32_16x16x32_bf16 v[24:27], v[138:141], v[162:165], 0
	v_mfma_f32_16x16x32_bf16 v[28:31], v[154:157], v[162:165], 0
	v_mfma_f32_16x16x32_bf16 v[16:19], v[138:141], v[170:173], 0
	v_mfma_f32_16x16x32_bf16 v[20:23], v[154:157], v[170:173], 0
	v_mfma_f32_16x16x32_bf16 v[8:11], v[138:141], v[178:181], 0
	v_mfma_f32_16x16x32_bf16 v[12:15], v[154:157], v[178:181], 0
	v_mfma_f32_16x16x32_bf16 v[0:3], v[138:141], v[186:189], 0
	v_mfma_f32_16x16x32_bf16 v[4:7], v[154:157], v[186:189], 0
	v_mfma_f32_16x16x32_bf16 v[24:27], v[150:153], v[166:169], v[24:27]
	v_mfma_f32_16x16x32_bf16 v[28:31], v[158:161], v[166:169], v[28:31]
	v_mfma_f32_16x16x32_bf16 v[16:19], v[150:153], v[174:177], v[16:19]
	v_mfma_f32_16x16x32_bf16 v[20:23], v[158:161], v[174:177], v[20:23]
	v_mfma_f32_16x16x32_bf16 v[8:11], v[150:153], v[182:185], v[8:11]
	v_mfma_f32_16x16x32_bf16 v[12:15], v[158:161], v[182:185], v[12:15]
	v_mfma_f32_16x16x32_bf16 v[0:3], v[150:153], v[190:193], v[0:3]
	v_mfma_f32_16x16x32_bf16 v[4:7], v[158:161], v[190:193], v[4:7]
	s_barrier
	s_setprio 0
	s_add_i32 s89, 0, 0x14000
	s_add_i32 vcc_lo, s26, s4
	s_mov_b32 m0, vcc_lo
	ds_read_b128 v[194:197], v213
	ds_read_b128 v[200:203], v213 offset:1024
	ds_read_b128 v[204:207], v213 offset:2048
	ds_read_b128 v[208:211], v213 offset:3072
	global_load_lds_dwordx4 v198, s[22:23]
	s_add_i32 m0, vcc_lo, 0x2000
	s_nop 0
	global_load_lds_dwordx4 v128, s[22:23]
	s_setprio 1
	s_barrier
	s_waitcnt lgkmcnt(0)
	v_mfma_f32_16x16x32_bf16 v[88:91], v[194:197], v[162:165], 0
	v_mfma_f32_16x16x32_bf16 v[96:99], v[204:207], v[162:165], 0
	v_mfma_f32_16x16x32_bf16 v[80:83], v[194:197], v[170:173], 0
	v_mfma_f32_16x16x32_bf16 v[84:87], v[204:207], v[170:173], 0
	v_mfma_f32_16x16x32_bf16 v[72:75], v[194:197], v[178:181], 0
	v_mfma_f32_16x16x32_bf16 v[76:79], v[204:207], v[178:181], 0
	v_mfma_f32_16x16x32_bf16 v[56:59], v[194:197], v[186:189], 0
	v_mfma_f32_16x16x32_bf16 v[64:67], v[204:207], v[186:189], 0
	v_mfma_f32_16x16x32_bf16 v[88:91], v[200:203], v[166:169], v[88:91]
	v_mfma_f32_16x16x32_bf16 v[96:99], v[208:211], v[166:169], v[96:99]
	v_mfma_f32_16x16x32_bf16 v[80:83], v[200:203], v[174:177], v[80:83]
	v_mfma_f32_16x16x32_bf16 v[84:87], v[208:211], v[174:177], v[84:87]
	v_mfma_f32_16x16x32_bf16 v[72:75], v[200:203], v[182:185], v[72:75]
	v_mfma_f32_16x16x32_bf16 v[76:79], v[208:211], v[182:185], v[76:79]
	v_mfma_f32_16x16x32_bf16 v[56:59], v[200:203], v[190:193], v[56:59]
	v_mfma_f32_16x16x32_bf16 v[64:67], v[208:211], v[190:193], v[64:67]
	s_barrier
	s_setprio 0
	s_mov_b32 m0, s49
	ds_read_b128 v[162:165], v148 offset:16384
	ds_read_b128 v[166:169], v148 offset:17408
	ds_read_b128 v[170:173], v148 offset:18432
	ds_read_b128 v[174:177], v148 offset:19456
	ds_read_b128 v[178:181], v148 offset:20480
	ds_read_b128 v[182:185], v148 offset:21504
	ds_read_b128 v[186:189], v148 offset:22528
	ds_read_b128 v[190:193], v148 offset:23552
	global_load_lds_dwordx4 v132, s[18:19]
	s_mov_b32 m0, s52
	s_nop 0
	global_load_lds_dwordx4 v130, s[18:19]
	s_setprio 1
	s_barrier
	s_waitcnt lgkmcnt(0)
	v_mfma_f32_16x16x32_bf16 v[60:63], v[138:141], v[162:165], 0
	v_mfma_f32_16x16x32_bf16 v[68:71], v[154:157], v[162:165], 0
	v_mfma_f32_16x16x32_bf16 v[48:51], v[138:141], v[170:173], 0
	v_mfma_f32_16x16x32_bf16 v[52:55], v[154:157], v[170:173], 0
	v_mfma_f32_16x16x32_bf16 v[40:43], v[138:141], v[178:181], 0
	v_mfma_f32_16x16x32_bf16 v[44:47], v[154:157], v[178:181], 0
	v_mfma_f32_16x16x32_bf16 v[32:35], v[138:141], v[186:189], 0
	v_mfma_f32_16x16x32_bf16 v[36:39], v[154:157], v[186:189], 0
	v_mfma_f32_16x16x32_bf16 v[60:63], v[150:153], v[166:169], v[60:63]
	v_mfma_f32_16x16x32_bf16 v[68:71], v[158:161], v[166:169], v[68:71]
	v_mfma_f32_16x16x32_bf16 v[48:51], v[150:153], v[174:177], v[48:51]
	v_mfma_f32_16x16x32_bf16 v[52:55], v[158:161], v[174:177], v[52:55]
	v_mfma_f32_16x16x32_bf16 v[40:43], v[150:153], v[182:185], v[40:43]
	v_mfma_f32_16x16x32_bf16 v[44:47], v[158:161], v[182:185], v[44:47]
	v_mfma_f32_16x16x32_bf16 v[32:35], v[150:153], v[190:193], v[32:35]
	v_mfma_f32_16x16x32_bf16 v[36:39], v[158:161], v[190:193], v[36:39]
	s_barrier
	s_setprio 0
	s_add_u32 s22, s22, s84
	s_addc_u32 s23, s23, 0
	s_add_i32 s89, s89, s4
	s_mov_b32 m0, s89
	s_nop 0
	global_load_lds_dwordx4 v198, s[22:23]
	s_add_i32 m0, s89, 0x2000
	s_nop 0
	global_load_lds_dwordx4 v128, s[22:23]
	s_add_i32 s22, 0, 0x18000
	s_waitcnt vmcnt(6)
	s_setprio 1
	s_barrier
; #define PG8_STAGE(bufoff, gbase, voff) do { _Pragma("unroll") for (int _i = 0; _i < 2; ++_i) \
;         __builtin_amdgcn_global_load_lds((const unsigned*)((const char*)(gbase) + (voff)[_i]), (LAS unsigned*)(lds + (bufoff) + ldsw + _i * 8192), 16, 0, 0); } while (0)
; #define PG8_LDA(dst, b, h) do { _Pragma("unroll") for (int m = 0; m < 4; ++m) _Pragma("unroll") for (int k = 0; k < 2; ++k) dst[m][k] = *(const LAS bf16x8*)(lds + PG8_SA(b, h) + aoff + m * 2048 + k * 1024); } while (0)
; #define PG8_LDB(dst, b, h) do { _Pragma("unroll") for (int n = 0; n < 2; ++n) _Pragma("unroll") for (int k = 0; k < 2; ++k) dst[n][k] = *(const LAS bf16x8*)(lds + PG8_SB(b, h) + boff + n * 2048 + k * 1024); } while (0)
; #define PG8_MMA(ai, bj, At, Bt) do { __builtin_amdgcn_s_setprio(1); _Pragma("unroll") for (int m = 0; m < 4; ++m) _Pragma("unroll") for (int n = 0; n < 2; ++n) _Pragma("unroll") for (int k = 0; k < 2; ++k) \
;         acc[ai][bj][m][n] = __builtin_amdgcn_mfma_f32_16x16x32_bf16(Bt[n][k], At[m][k], acc[ai][bj][m][n], 0, 0, 0); __builtin_amdgcn_s_setprio(0); } while (0)
; #define PG8_WAIT_V(n) asm volatile("s_waitcnt vmcnt(" #n ")" ::: "memory")
; #define PG8_WAIT_L(n) asm volatile("s_waitcnt lgkmcnt(" #n ")" ::: "memory")
; #define PG8_BAR __builtin_amdgcn_s_barrier()
; #define PG8_SCHED __builtin_amdgcn_sched_barrier(0)
; template <class Epi>
; DI void gemm_phase(LAS unsigned char* lds, const Gemm g, const StaticOrder& S, const Epi& E, const int tid) {
;     ...
;             PG8_WAIT_V(6); PG8_BAR; PG8_MMA(1, 1, At, B1); PG8_BAR;
;             PG8_LDB(B0, 1, 0); PG8_SCHED; PG8_LDA(At, 1, 0); PG8_STAGE(PG8_SA(0, 1), a2 + hstep, voffA);
;             PG8_WAIT_L(8); PG8_BAR; PG8_WAIT_L(0); PG8_MMA(0, 0, At, B0); PG8_BAR; PG8_SCHED;
;             PG8_LDB(B1, 1, 1); PG8_STAGE(PG8_SB(1, 0), b3, voffB);
;             PG8_BAR; PG8_WAIT_L(0); PG8_MMA(0, 1, At, B1); PG8_BAR;
;             PG8_LDA(At, 1, 1); PG8_STAGE(PG8_SA(1, 0), a3, voffA);
	v_mfma_f32_16x16x32_bf16 v[120:123], v[194:197], v[162:165], 0
	v_mfma_f32_16x16x32_bf16 v[124:127], v[204:207], v[162:165], 0
	v_mfma_f32_16x16x32_bf16 v[112:115], v[194:197], v[170:173], 0
	v_mfma_f32_16x16x32_bf16 v[116:119], v[204:207], v[170:173], 0
	v_mfma_f32_16x16x32_bf16 v[104:107], v[194:197], v[178:181], 0
	v_mfma_f32_16x16x32_bf16 v[108:111], v[204:207], v[178:181], 0
	v_mfma_f32_16x16x32_bf16 v[92:95], v[194:197], v[186:189], 0
	v_mfma_f32_16x16x32_bf16 v[100:103], v[204:207], v[186:189], 0
	v_mfma_f32_16x16x32_bf16 v[120:123], v[200:203], v[166:169], v[120:123]
	v_mfma_f32_16x16x32_bf16 v[124:127], v[208:211], v[166:169], v[124:127]
	v_mfma_f32_16x16x32_bf16 v[112:115], v[200:203], v[174:177], v[112:115]
	v_mfma_f32_16x16x32_bf16 v[116:119], v[208:211], v[174:177], v[116:119]
	v_mfma_f32_16x16x32_bf16 v[104:107], v[200:203], v[182:185], v[104:107]
	v_mfma_f32_16x16x32_bf16 v[108:111], v[208:211], v[182:185], v[108:111]
	v_mfma_f32_16x16x32_bf16 v[92:95], v[200:203], v[190:193], v[92:95]
	v_mfma_f32_16x16x32_bf16 v[100:103], v[208:211], v[190:193], v[100:103]
	s_barrier
	s_setprio 0
	ds_read_b128 v[138:141], v214
	ds_read_b128 v[150:153], v214 offset:1024
	ds_read_b128 v[154:157], v214 offset:2048
	ds_read_b128 v[158:161], v214 offset:3072
	s_add_u32 s18, s18, s84
	s_addc_u32 s19, s19, 0
	s_mov_b32 m0, s53
	ds_read_b128 v[162:165], v148 offset:32768
	ds_read_b128 v[166:169], v148 offset:33792
	ds_read_b128 v[170:173], v148 offset:34816
	ds_read_b128 v[174:177], v148 offset:35840
	ds_read_b128 v[178:181], v148 offset:36864
	ds_read_b128 v[182:185], v148 offset:37888
	ds_read_b128 v[186:189], v148 offset:38912
	ds_read_b128 v[190:193], v148 offset:39936
	global_load_lds_dwordx4 v132, s[18:19]
	s_mov_b32 m0, s54
	s_nop 0
	global_load_lds_dwordx4 v130, s[18:19]
	s_waitcnt lgkmcnt(8)
	s_setprio 1
	s_barrier
	s_waitcnt lgkmcnt(0)
	v_mfma_f32_16x16x32_bf16 v[24:27], v[138:141], v[162:165], v[24:27]
	v_mfma_f32_16x16x32_bf16 v[28:31], v[154:157], v[162:165], v[28:31]
	v_mfma_f32_16x16x32_bf16 v[16:19], v[138:141], v[170:173], v[16:19]
	v_mfma_f32_16x16x32_bf16 v[20:23], v[154:157], v[170:173], v[20:23]
	v_mfma_f32_16x16x32_bf16 v[8:11], v[138:141], v[178:181], v[8:11]
	v_mfma_f32_16x16x32_bf16 v[12:15], v[154:157], v[178:181], v[12:15]
	v_mfma_f32_16x16x32_bf16 v[0:3], v[138:141], v[186:189], v[0:3]
	v_mfma_f32_16x16x32_bf16 v[4:7], v[154:157], v[186:189], v[4:7]
	v_mfma_f32_16x16x32_bf16 v[24:27], v[150:153], v[166:169], v[24:27]
	v_mfma_f32_16x16x32_bf16 v[28:31], v[158:161], v[166:169], v[28:31]
	v_mfma_f32_16x16x32_bf16 v[16:19], v[150:153], v[174:177], v[16:19]
	v_mfma_f32_16x16x32_bf16 v[20:23], v[158:161], v[174:177], v[20:23]
	v_mfma_f32_16x16x32_bf16 v[8:11], v[150:153], v[182:185], v[8:11]
	v_mfma_f32_16x16x32_bf16 v[12:15], v[158:161], v[182:185], v[12:15]
	v_mfma_f32_16x16x32_bf16 v[0:3], v[150:153], v[190:193], v[0:3]
	v_mfma_f32_16x16x32_bf16 v[4:7], v[158:161], v[190:193], v[4:7]
	s_barrier
	s_setprio 0
	s_add_i32 s18, 0, 0x1c000
	s_add_i32 s19, s22, s4
	s_mov_b32 m0, s19
	ds_read_b128 v[194:197], v215
	ds_read_b128 v[200:203], v215 offset:1024
	ds_read_b128 v[204:207], v215 offset:2048
	ds_read_b128 v[208:211], v215 offset:3072
	s_add_i32 vcc_hi, s60, 2
	s_cmp_eq_u32 vcc_hi, s83
	s_cselect_b32 s100, s16, s81
	s_cselect_b32 s101, s17, s82
	s_add_u32 s100, s100, 0x80
	s_addc_u32 s101, s101, 0
	global_load_lds_dwordx4 v198, s[100:101]
	s_add_i32 m0, s19, 0x2000
	s_nop 0
	global_load_lds_dwordx4 v128, s[100:101]
	s_setprio 1
	s_barrier
	s_waitcnt lgkmcnt(0)
	v_mfma_f32_16x16x32_bf16 v[88:91], v[194:197], v[162:165], v[88:91]
	v_mfma_f32_16x16x32_bf16 v[96:99], v[204:207], v[162:165], v[96:99]
	v_mfma_f32_16x16x32_bf16 v[80:83], v[194:197], v[170:173], v[80:83]
	v_mfma_f32_16x16x32_bf16 v[84:87], v[204:207], v[170:173], v[84:87]
	v_mfma_f32_16x16x32_bf16 v[72:75], v[194:197], v[178:181], v[72:75]
	v_mfma_f32_16x16x32_bf16 v[76:79], v[204:207], v[178:181], v[76:79]
	v_mfma_f32_16x16x32_bf16 v[56:59], v[194:197], v[186:189], v[56:59]
	v_mfma_f32_16x16x32_bf16 v[64:67], v[204:207], v[186:189], v[64:67]
	v_mfma_f32_16x16x32_bf16 v[88:91], v[200:203], v[166:169], v[88:91]
	v_mfma_f32_16x16x32_bf16 v[96:99], v[208:211], v[166:169], v[96:99]
	v_mfma_f32_16x16x32_bf16 v[80:83], v[200:203], v[174:177], v[80:83]
	v_mfma_f32_16x16x32_bf16 v[84:87], v[208:211], v[174:177], v[84:87]
	v_mfma_f32_16x16x32_bf16 v[72:75], v[200:203], v[182:185], v[72:75]
	v_mfma_f32_16x16x32_bf16 v[76:79], v[208:211], v[182:185], v[76:79]
	v_mfma_f32_16x16x32_bf16 v[56:59], v[200:203], v[190:193], v[56:59]
	v_mfma_f32_16x16x32_bf16 v[64:67], v[208:211], v[190:193], v[64:67]
	s_barrier
	s_setprio 0
	s_mov_b32 m0, s55
	ds_read_b128 v[162:165], v148 offset:49152
	ds_read_b128 v[166:169], v148 offset:50176
	ds_read_b128 v[170:173], v148 offset:51200
	ds_read_b128 v[174:177], v148 offset:52224
	ds_read_b128 v[178:181], v148 offset:53248
	ds_read_b128 v[182:185], v148 offset:54272
	ds_read_b128 v[186:189], v148 offset:55296
	ds_read_b128 v[190:193], v148 offset:56320
	s_add_u32 s100, s20, 0x80
	s_addc_u32 s101, s21, 0
	s_add_i32 vcc_hi, s60, 2
	s_cmp_eq_u32 vcc_hi, s83
	s_cselect_b32 s100, s8, s100
	s_cselect_b32 s101, s9, s101
	s_add_u32 s100, s100, 0x80
	s_addc_u32 s101, s101, 0
	global_load_lds_dwordx4 v132, s[100:101]
	s_mov_b32 m0, s56
	s_nop 0
	global_load_lds_dwordx4 v130, s[100:101]
	s_setprio 1
	s_barrier
; #define PG8_STAGE(bufoff, gbase, voff) do { _Pragma("unroll") for (int _i = 0; _i < 2; ++_i) \
;         __builtin_amdgcn_global_load_lds((const unsigned*)((const char*)(gbase) + (voff)[_i]), (LAS unsigned*)(lds + (bufoff) + ldsw + _i * 8192), 16, 0, 0); } while (0)
; #define PG8_LDA(dst, b, h) do { _Pragma("unroll") for (int m = 0; m < 4; ++m) _Pragma("unroll") for (int k = 0; k < 2; ++k) dst[m][k] = *(const LAS bf16x8*)(lds + PG8_SA(b, h) + aoff + m * 2048 + k * 1024); } while (0)
; #define PG8_LDB(dst, b, h) do { _Pragma("unroll") for (int n = 0; n < 2; ++n) _Pragma("unroll") for (int k = 0; k < 2; ++k) dst[n][k] = *(const LAS bf16x8*)(lds + PG8_SB(b, h) + boff + n * 2048 + k * 1024); } while (0)
; #define PG8_MMA(ai, bj, At, Bt) do { __builtin_amdgcn_s_setprio(1); _Pragma("unroll") for (int m = 0; m < 4; ++m) _Pragma("unroll") for (int n = 0; n < 2; ++n) _Pragma("unroll") for (int k = 0; k < 2; ++k) \
;         acc[ai][bj][m][n] = __builtin_amdgcn_mfma_f32_16x16x32_bf16(Bt[n][k], At[m][k], acc[ai][bj][m][n], 0, 0, 0); __builtin_amdgcn_s_setprio(0); } while (0)
; #define PG8_WAIT_V(n) asm volatile("s_waitcnt vmcnt(" #n ")" ::: "memory")
; #define PG8_WAIT_L(n) asm volatile("s_waitcnt lgkmcnt(" #n ")" ::: "memory")
; #define PG8_BAR __builtin_amdgcn_s_barrier()
; #define PG8_SCHED __builtin_amdgcn_sched_barrier(0)
; template <class Epi>
; DI void gemm_phase(LAS unsigned char* lds, const Gemm g, const StaticOrder& S, const Epi& E, const int tid) {
;     ...
;             PG8_LDB(B0, 0, 0); PG8_SCHED; PG8_LDA(At, 0, 0); PG8_STAGE(PG8_SA(1, 1), a1 + hstep, voffA);
;             PG8_WAIT_L(8); PG8_BAR; PG8_WAIT_L(0); PG8_MMA(0, 0, At, B0); PG8_BAR; PG8_SCHED;
;             PG8_LDB(B1, 0, 1); PG8_STAGE(PG8_SB(0, 0), b2, voffB);
;     ...
;             PG8_LDA(At, 1, 1); PG8_STAGE(PG8_SA(1, 0), a3, voffA);
;             PG8_BAR; PG8_WAIT_L(0); PG8_MMA(1, 0, At, B0); PG8_BAR; PG8_SCHED;
;             PG8_STAGE(PG8_SB(1, 1), b3 + hstep, voffB);
;             PG8_WAIT_V(6); PG8_BAR; PG8_MMA(1, 1, At, B1); PG8_BAR;
	s_waitcnt lgkmcnt(0)
	v_mfma_f32_16x16x32_bf16 v[60:63], v[138:141], v[162:165], v[60:63]
	v_mfma_f32_16x16x32_bf16 v[68:71], v[154:157], v[162:165], v[68:71]
	v_mfma_f32_16x16x32_bf16 v[48:51], v[138:141], v[170:173], v[48:51]
	v_mfma_f32_16x16x32_bf16 v[52:55], v[154:157], v[170:173], v[52:55]
	v_mfma_f32_16x16x32_bf16 v[40:43], v[138:141], v[178:181], v[40:43]
	v_mfma_f32_16x16x32_bf16 v[44:47], v[154:157], v[178:181], v[44:47]
	v_mfma_f32_16x16x32_bf16 v[32:35], v[138:141], v[186:189], v[32:35]
	v_mfma_f32_16x16x32_bf16 v[36:39], v[154:157], v[186:189], v[36:39]
	v_mfma_f32_16x16x32_bf16 v[60:63], v[150:153], v[166:169], v[60:63]
	v_mfma_f32_16x16x32_bf16 v[68:71], v[158:161], v[166:169], v[68:71]
	v_mfma_f32_16x16x32_bf16 v[48:51], v[150:153], v[174:177], v[48:51]
	v_mfma_f32_16x16x32_bf16 v[52:55], v[158:161], v[174:177], v[52:55]
	v_mfma_f32_16x16x32_bf16 v[40:43], v[150:153], v[182:185], v[40:43]
	v_mfma_f32_16x16x32_bf16 v[44:47], v[158:161], v[182:185], v[44:47]
	v_mfma_f32_16x16x32_bf16 v[32:35], v[150:153], v[190:193], v[32:35]
	v_mfma_f32_16x16x32_bf16 v[36:39], v[158:161], v[190:193], v[36:39]
	s_barrier
	s_setprio 0
	s_add_i32 s18, s18, s4
	s_add_i32 vcc_hi, s60, 2
	s_cmp_eq_u32 vcc_hi, s83
	s_cselect_b32 s100, s16, s81
	s_cselect_b32 s101, s17, s82
	s_add_u32 s100, s100, s84
	s_addc_u32 s101, s101, 0
	s_add_u32 s100, s100, 0x80
	s_addc_u32 s101, s101, 0
	s_mov_b32 m0, s18
	s_nop 0
	global_load_lds_dwordx4 v198, s[100:101]
	s_add_i32 m0, s18, 0x2000
	s_nop 0
	global_load_lds_dwordx4 v128, s[100:101]
	s_add_u32 s20, s20, 0x100
	s_addc_u32 s21, s21, 0
	s_add_u32 s81, s81, 0x100
	s_addc_u32 s82, s82, 0
	s_mov_b32 s18, s83
	s_cmp_ge_u32 s83, s57
	s_waitcnt vmcnt(6)
	s_setprio 1
	s_barrier
	v_mfma_f32_16x16x32_bf16 v[120:123], v[194:197], v[162:165], v[120:123]
	v_mfma_f32_16x16x32_bf16 v[124:127], v[204:207], v[162:165], v[124:127]
	v_mfma_f32_16x16x32_bf16 v[112:115], v[194:197], v[170:173], v[112:115]
	v_mfma_f32_16x16x32_bf16 v[116:119], v[204:207], v[170:173], v[116:119]
	v_mfma_f32_16x16x32_bf16 v[104:107], v[194:197], v[178:181], v[104:107]
	v_mfma_f32_16x16x32_bf16 v[108:111], v[204:207], v[178:181], v[108:111]
	v_mfma_f32_16x16x32_bf16 v[92:95], v[194:197], v[186:189], v[92:95]
	v_mfma_f32_16x16x32_bf16 v[100:103], v[204:207], v[186:189], v[100:103]
	v_mfma_f32_16x16x32_bf16 v[120:123], v[200:203], v[166:169], v[120:123]
	v_mfma_f32_16x16x32_bf16 v[124:127], v[208:211], v[166:169], v[124:127]
	v_mfma_f32_16x16x32_bf16 v[112:115], v[200:203], v[174:177], v[112:115]
	v_mfma_f32_16x16x32_bf16 v[116:119], v[208:211], v[174:177], v[116:119]
	v_mfma_f32_16x16x32_bf16 v[104:107], v[200:203], v[182:185], v[104:107]
	v_mfma_f32_16x16x32_bf16 v[108:111], v[208:211], v[182:185], v[108:111]
	v_mfma_f32_16x16x32_bf16 v[92:95], v[200:203], v[190:193], v[92:95]
	v_mfma_f32_16x16x32_bf16 v[100:103], v[208:211], v[190:193], v[100:103]
	s_barrier
	s_setprio 0
	s_cbranch_scc0 .LBB0_743
	s_branch .Lgemm_epi
.LBB0_743:
	ds_read_b128 v[138:141], v212
	ds_read_b128 v[150:153], v212 offset:1024
	ds_read_b128 v[154:157], v212 offset:2048
	ds_read_b128 v[158:161], v212 offset:3072
	s_add_i32 s83, s18, 2
	s_add_u32 s22, s20, 0x80
	s_addc_u32 s19, s21, 0
	s_cmp_eq_u32 s60, s18
	s_cselect_b32 s18, s8, s22
	s_cselect_b32 s19, s9, s19
	s_cselect_b32 s23, s17, s82
	s_cselect_b32 s22, s16, s81
	s_add_i32 m0, s49, 0xc000
	ds_read_b128 v[162:165], v148
	ds_read_b128 v[166:169], v148 offset:1024
	ds_read_b128 v[170:173], v148 offset:2048
	ds_read_b128 v[174:177], v148 offset:3072
	ds_read_b128 v[178:181], v148 offset:4096
	ds_read_b128 v[182:185], v148 offset:5120
	ds_read_b128 v[186:189], v148 offset:6144
	ds_read_b128 v[190:193], v148 offset:7168
	global_load_lds_dwordx4 v134, s[20:21]
	s_add_i32 m0, s49, 0xe000
	s_nop 0
	global_load_lds_dwordx4 v136, s[20:21]
	s_waitcnt lgkmcnt(8)
	s_setprio 1
	s_barrier
	s_waitcnt lgkmcnt(0)
	v_mfma_f32_16x16x32_bf16 v[24:27], v[138:141], v[162:165], v[24:27]
	v_mfma_f32_16x16x32_bf16 v[28:31], v[154:157], v[162:165], v[28:31]
	v_mfma_f32_16x16x32_bf16 v[16:19], v[138:141], v[170:173], v[16:19]
	v_mfma_f32_16x16x32_bf16 v[20:23], v[154:157], v[170:173], v[20:23]
	v_mfma_f32_16x16x32_bf16 v[8:11], v[138:141], v[178:181], v[8:11]
	v_mfma_f32_16x16x32_bf16 v[12:15], v[154:157], v[178:181], v[12:15]
	v_mfma_f32_16x16x32_bf16 v[0:3], v[138:141], v[186:189], v[0:3]
	v_mfma_f32_16x16x32_bf16 v[4:7], v[154:157], v[186:189], v[4:7]
	v_mfma_f32_16x16x32_bf16 v[24:27], v[150:153], v[166:169], v[24:27]
	v_mfma_f32_16x16x32_bf16 v[28:31], v[158:161], v[166:169], v[28:31]
	v_mfma_f32_16x16x32_bf16 v[16:19], v[150:153], v[174:177], v[16:19]
	v_mfma_f32_16x16x32_bf16 v[20:23], v[158:161], v[174:177], v[20:23]
	v_mfma_f32_16x16x32_bf16 v[8:11], v[150:153], v[182:185], v[8:11]
	v_mfma_f32_16x16x32_bf16 v[12:15], v[158:161], v[182:185], v[12:15]
	v_mfma_f32_16x16x32_bf16 v[0:3], v[150:153], v[190:193], v[0:3]
	v_mfma_f32_16x16x32_bf16 v[4:7], v[158:161], v[190:193], v[4:7]
	s_barrier
	s_setprio 0
	s_add_i32 s89, 0, 0x14000
	s_add_i32 vcc_lo, s26, s4
	s_mov_b32 m0, vcc_lo
	ds_read_b128 v[194:197], v213
	ds_read_b128 v[200:203], v213 offset:1024
	ds_read_b128 v[204:207], v213 offset:2048
	ds_read_b128 v[208:211], v213 offset:3072
	global_load_lds_dwordx4 v198, s[22:23]
	s_add_i32 m0, vcc_lo, 0x2000
	s_nop 0
	global_load_lds_dwordx4 v128, s[22:23]
	s_setprio 1
	s_barrier
; #define PG8_STAGE(bufoff, gbase, voff) do { _Pragma("unroll") for (int _i = 0; _i < 2; ++_i) \
;         __builtin_amdgcn_global_load_lds((const unsigned*)((const char*)(gbase) + (voff)[_i]), (LAS unsigned*)(lds + (bufoff) + ldsw + _i * 8192), 16, 0, 0); } while (0)
; #define PG8_LDA(dst, b, h) do { _Pragma("unroll") for (int m = 0; m < 4; ++m) _Pragma("unroll") for (int k = 0; k < 2; ++k) dst[m][k] = *(const LAS bf16x8*)(lds + PG8_SA(b, h) + aoff + m * 2048 + k * 1024); } while (0)
; #define PG8_LDB(dst, b, h) do { _Pragma("unroll") for (int n = 0; n < 2; ++n) _Pragma("unroll") for (int k = 0; k < 2; ++k) dst[n][k] = *(const LAS bf16x8*)(lds + PG8_SB(b, h) + boff + n * 2048 + k * 1024); } while (0)
; #define PG8_MMA(ai, bj, At, Bt) do { __builtin_amdgcn_s_setprio(1); _Pragma("unroll") for (int m = 0; m < 4; ++m) _Pragma("unroll") for (int n = 0; n < 2; ++n) _Pragma("unroll") for (int k = 0; k < 2; ++k) \
;         acc[ai][bj][m][n] = __builtin_amdgcn_mfma_f32_16x16x32_bf16(Bt[n][k], At[m][k], acc[ai][bj][m][n], 0, 0, 0); __builtin_amdgcn_s_setprio(0); } while (0)
; #define PG8_WAIT_V(n) asm volatile("s_waitcnt vmcnt(" #n ")" ::: "memory")
; #define PG8_WAIT_L(n) asm volatile("s_waitcnt lgkmcnt(" #n ")" ::: "memory")
; #define PG8_BAR __builtin_amdgcn_s_barrier()
; #define PG8_SCHED __builtin_amdgcn_sched_barrier(0)
; template <class Epi>
; DI void gemm_phase(LAS unsigned char* lds, const Gemm g, const StaticOrder& S, const Epi& E, const int tid) {
;     ...
;             PG8_BAR; PG8_WAIT_L(0); PG8_MMA(0, 1, At, B1); PG8_BAR;
;             PG8_LDA(At, 0, 1); PG8_STAGE(PG8_SA(0, 0), a2, voffA);
;             PG8_BAR; PG8_WAIT_L(0); PG8_MMA(1, 0, At, B0); PG8_BAR; PG8_SCHED;
;             PG8_STAGE(PG8_SB(0, 1), b2 + hstep, voffB);
;             PG8_WAIT_V(6); PG8_BAR; PG8_MMA(1, 1, At, B1); PG8_BAR;
;             PG8_LDB(B0, 1, 0); PG8_SCHED; PG8_LDA(At, 1, 0); PG8_STAGE(PG8_SA(0, 1), a2 + hstep, voffA);
;             PG8_WAIT_L(8); PG8_BAR; PG8_WAIT_L(0); PG8_MMA(0, 0, At, B0); PG8_BAR; PG8_SCHED;
;             PG8_LDB(B1, 1, 1); PG8_STAGE(PG8_SB(1, 0), b3, voffB);
;             PG8_BAR; PG8_WAIT_L(0); PG8_MMA(0, 1, At, B1); PG8_BAR;
	s_waitcnt lgkmcnt(0)
	v_mfma_f32_16x16x32_bf16 v[88:91], v[194:197], v[162:165], v[88:91]
	v_mfma_f32_16x16x32_bf16 v[96:99], v[204:207], v[162:165], v[96:99]
	v_mfma_f32_16x16x32_bf16 v[80:83], v[194:197], v[170:173], v[80:83]
	v_mfma_f32_16x16x32_bf16 v[84:87], v[204:207], v[170:173], v[84:87]
	v_mfma_f32_16x16x32_bf16 v[72:75], v[194:197], v[178:181], v[72:75]
	v_mfma_f32_16x16x32_bf16 v[76:79], v[204:207], v[178:181], v[76:79]
	v_mfma_f32_16x16x32_bf16 v[56:59], v[194:197], v[186:189], v[56:59]
	v_mfma_f32_16x16x32_bf16 v[64:67], v[204:207], v[186:189], v[64:67]
	v_mfma_f32_16x16x32_bf16 v[88:91], v[200:203], v[166:169], v[88:91]
	v_mfma_f32_16x16x32_bf16 v[96:99], v[208:211], v[166:169], v[96:99]
	v_mfma_f32_16x16x32_bf16 v[80:83], v[200:203], v[174:177], v[80:83]
	v_mfma_f32_16x16x32_bf16 v[84:87], v[208:211], v[174:177], v[84:87]
	v_mfma_f32_16x16x32_bf16 v[72:75], v[200:203], v[182:185], v[72:75]
	v_mfma_f32_16x16x32_bf16 v[76:79], v[208:211], v[182:185], v[76:79]
	v_mfma_f32_16x16x32_bf16 v[56:59], v[200:203], v[190:193], v[56:59]
	v_mfma_f32_16x16x32_bf16 v[64:67], v[208:211], v[190:193], v[64:67]
	s_barrier
	s_setprio 0
	s_mov_b32 m0, s49
	ds_read_b128 v[162:165], v148 offset:16384
	ds_read_b128 v[166:169], v148 offset:17408
	ds_read_b128 v[170:173], v148 offset:18432
	ds_read_b128 v[174:177], v148 offset:19456
	ds_read_b128 v[178:181], v148 offset:20480
	ds_read_b128 v[182:185], v148 offset:21504
	ds_read_b128 v[186:189], v148 offset:22528
	ds_read_b128 v[190:193], v148 offset:23552
	global_load_lds_dwordx4 v132, s[18:19]
	s_mov_b32 m0, s52
	s_nop 0
	global_load_lds_dwordx4 v130, s[18:19]
	s_setprio 1
	s_barrier
	s_waitcnt lgkmcnt(0)
	v_mfma_f32_16x16x32_bf16 v[60:63], v[138:141], v[162:165], v[60:63]
	v_mfma_f32_16x16x32_bf16 v[68:71], v[154:157], v[162:165], v[68:71]
	v_mfma_f32_16x16x32_bf16 v[48:51], v[138:141], v[170:173], v[48:51]
	v_mfma_f32_16x16x32_bf16 v[52:55], v[154:157], v[170:173], v[52:55]
	v_mfma_f32_16x16x32_bf16 v[40:43], v[138:141], v[178:181], v[40:43]
	v_mfma_f32_16x16x32_bf16 v[44:47], v[154:157], v[178:181], v[44:47]
	v_mfma_f32_16x16x32_bf16 v[32:35], v[138:141], v[186:189], v[32:35]
	v_mfma_f32_16x16x32_bf16 v[36:39], v[154:157], v[186:189], v[36:39]
	v_mfma_f32_16x16x32_bf16 v[60:63], v[150:153], v[166:169], v[60:63]
	v_mfma_f32_16x16x32_bf16 v[68:71], v[158:161], v[166:169], v[68:71]
	v_mfma_f32_16x16x32_bf16 v[48:51], v[150:153], v[174:177], v[48:51]
	v_mfma_f32_16x16x32_bf16 v[52:55], v[158:161], v[174:177], v[52:55]
	v_mfma_f32_16x16x32_bf16 v[40:43], v[150:153], v[182:185], v[40:43]
	v_mfma_f32_16x16x32_bf16 v[44:47], v[158:161], v[182:185], v[44:47]
	v_mfma_f32_16x16x32_bf16 v[32:35], v[150:153], v[190:193], v[32:35]
	v_mfma_f32_16x16x32_bf16 v[36:39], v[158:161], v[190:193], v[36:39]
	s_barrier
	s_setprio 0
	s_add_u32 s22, s22, s84
	s_addc_u32 s23, s23, 0
	s_add_i32 s89, s89, s4
	s_mov_b32 m0, s89
	s_nop 0
	global_load_lds_dwordx4 v198, s[22:23]
	s_add_i32 m0, s89, 0x2000
	s_nop 0
	global_load_lds_dwordx4 v128, s[22:23]
	s_add_i32 s22, 0, 0x18000
	s_waitcnt vmcnt(6)
	s_setprio 1
	s_barrier
	v_mfma_f32_16x16x32_bf16 v[120:123], v[194:197], v[162:165], v[120:123]
	v_mfma_f32_16x16x32_bf16 v[124:127], v[204:207], v[162:165], v[124:127]
	v_mfma_f32_16x16x32_bf16 v[112:115], v[194:197], v[170:173], v[112:115]
	v_mfma_f32_16x16x32_bf16 v[116:119], v[204:207], v[170:173], v[116:119]
	v_mfma_f32_16x16x32_bf16 v[104:107], v[194:197], v[178:181], v[104:107]
	v_mfma_f32_16x16x32_bf16 v[108:111], v[204:207], v[178:181], v[108:111]
	v_mfma_f32_16x16x32_bf16 v[92:95], v[194:197], v[186:189], v[92:95]
	v_mfma_f32_16x16x32_bf16 v[100:103], v[204:207], v[186:189], v[100:103]
	v_mfma_f32_16x16x32_bf16 v[120:123], v[200:203], v[166:169], v[120:123]
	v_mfma_f32_16x16x32_bf16 v[124:127], v[208:211], v[166:169], v[124:127]
	v_mfma_f32_16x16x32_bf16 v[112:115], v[200:203], v[174:177], v[112:115]
	v_mfma_f32_16x16x32_bf16 v[116:119], v[208:211], v[174:177], v[116:119]
	v_mfma_f32_16x16x32_bf16 v[104:107], v[200:203], v[182:185], v[104:107]
	v_mfma_f32_16x16x32_bf16 v[108:111], v[208:211], v[182:185], v[108:111]
	v_mfma_f32_16x16x32_bf16 v[92:95], v[200:203], v[190:193], v[92:95]
	v_mfma_f32_16x16x32_bf16 v[100:103], v[208:211], v[190:193], v[100:103]
	s_barrier
	s_setprio 0
	ds_read_b128 v[138:141], v214
	ds_read_b128 v[150:153], v214 offset:1024
	ds_read_b128 v[154:157], v214 offset:2048
	ds_read_b128 v[158:161], v214 offset:3072
	s_add_u32 s18, s18, s84
	s_addc_u32 s19, s19, 0
	s_mov_b32 m0, s53
	ds_read_b128 v[162:165], v148 offset:32768
	ds_read_b128 v[166:169], v148 offset:33792
	ds_read_b128 v[170:173], v148 offset:34816
	ds_read_b128 v[174:177], v148 offset:35840
	ds_read_b128 v[178:181], v148 offset:36864
	ds_read_b128 v[182:185], v148 offset:37888
	ds_read_b128 v[186:189], v148 offset:38912
	ds_read_b128 v[190:193], v148 offset:39936
	global_load_lds_dwordx4 v132, s[18:19]
	s_mov_b32 m0, s54
	s_nop 0
	global_load_lds_dwordx4 v130, s[18:19]
	s_waitcnt lgkmcnt(8)
	s_setprio 1
	s_barrier
	s_waitcnt lgkmcnt(0)
	v_mfma_f32_16x16x32_bf16 v[24:27], v[138:141], v[162:165], v[24:27]
	v_mfma_f32_16x16x32_bf16 v[28:31], v[154:157], v[162:165], v[28:31]
	v_mfma_f32_16x16x32_bf16 v[16:19], v[138:141], v[170:173], v[16:19]
	v_mfma_f32_16x16x32_bf16 v[20:23], v[154:157], v[170:173], v[20:23]
	v_mfma_f32_16x16x32_bf16 v[8:11], v[138:141], v[178:181], v[8:11]
	v_mfma_f32_16x16x32_bf16 v[12:15], v[154:157], v[178:181], v[12:15]
	v_mfma_f32_16x16x32_bf16 v[0:3], v[138:141], v[186:189], v[0:3]
	v_mfma_f32_16x16x32_bf16 v[4:7], v[154:157], v[186:189], v[4:7]
	v_mfma_f32_16x16x32_bf16 v[24:27], v[150:153], v[166:169], v[24:27]
	v_mfma_f32_16x16x32_bf16 v[28:31], v[158:161], v[166:169], v[28:31]
	v_mfma_f32_16x16x32_bf16 v[16:19], v[150:153], v[174:177], v[16:19]
	v_mfma_f32_16x16x32_bf16 v[20:23], v[158:161], v[174:177], v[20:23]
	v_mfma_f32_16x16x32_bf16 v[8:11], v[150:153], v[182:185], v[8:11]
	v_mfma_f32_16x16x32_bf16 v[12:15], v[158:161], v[182:185], v[12:15]
	v_mfma_f32_16x16x32_bf16 v[0:3], v[150:153], v[190:193], v[0:3]
	v_mfma_f32_16x16x32_bf16 v[4:7], v[158:161], v[190:193], v[4:7]
	s_barrier
; #define PG8_STAGE(bufoff, gbase, voff) do { _Pragma("unroll") for (int _i = 0; _i < 2; ++_i) \
;         __builtin_amdgcn_global_load_lds((const unsigned*)((const char*)(gbase) + (voff)[_i]), (LAS unsigned*)(lds + (bufoff) + ldsw + _i * 8192), 16, 0, 0); } while (0)
; #define PG8_LDA(dst, b, h) do { _Pragma("unroll") for (int m = 0; m < 4; ++m) _Pragma("unroll") for (int k = 0; k < 2; ++k) dst[m][k] = *(const LAS bf16x8*)(lds + PG8_SA(b, h) + aoff + m * 2048 + k * 1024); } while (0)
; #define PG8_LDB(dst, b, h) do { _Pragma("unroll") for (int n = 0; n < 2; ++n) _Pragma("unroll") for (int k = 0; k < 2; ++k) dst[n][k] = *(const LAS bf16x8*)(lds + PG8_SB(b, h) + boff + n * 2048 + k * 1024); } while (0)
; #define PG8_MMA(ai, bj, At, Bt) do { __builtin_amdgcn_s_setprio(1); _Pragma("unroll") for (int m = 0; m < 4; ++m) _Pragma("unroll") for (int n = 0; n < 2; ++n) _Pragma("unroll") for (int k = 0; k < 2; ++k) \
;         acc[ai][bj][m][n] = __builtin_amdgcn_mfma_f32_16x16x32_bf16(Bt[n][k], At[m][k], acc[ai][bj][m][n], 0, 0, 0); __builtin_amdgcn_s_setprio(0); } while (0)
; #define PG8_WAIT_V(n) asm volatile("s_waitcnt vmcnt(" #n ")" ::: "memory")
; #define PG8_WAIT_L(n) asm volatile("s_waitcnt lgkmcnt(" #n ")" ::: "memory")
; #define PG8_BAR __builtin_amdgcn_s_barrier()
; #define PG8_SCHED __builtin_amdgcn_sched_barrier(0)
; template <class Epi>
; DI void gemm_phase(LAS unsigned char* lds, const Gemm g, const StaticOrder& S, const Epi& E, const int tid) {
;     ...
;             PG8_LDB(B1, 1, 1); PG8_STAGE(PG8_SB(1, 0), b3, voffB);
;             PG8_BAR; PG8_WAIT_L(0); PG8_MMA(0, 1, At, B1); PG8_BAR;
;             PG8_LDA(At, 1, 1); PG8_STAGE(PG8_SA(1, 0), a3, voffA);
;             PG8_BAR; PG8_WAIT_L(0); PG8_MMA(1, 0, At, B0); PG8_BAR; PG8_SCHED;
;             PG8_STAGE(PG8_SB(1, 1), b3 + hstep, voffB);
;             PG8_WAIT_V(6); PG8_BAR; PG8_MMA(1, 1, At, B1); PG8_BAR;
	s_setprio 0
	s_add_i32 s18, 0, 0x1c000
	s_add_i32 s19, s22, s4
	s_mov_b32 m0, s19
	ds_read_b128 v[194:197], v215
	ds_read_b128 v[200:203], v215 offset:1024
	ds_read_b128 v[204:207], v215 offset:2048
	ds_read_b128 v[208:211], v215 offset:3072
	s_add_i32 vcc_hi, s60, 2
	s_cmp_eq_u32 vcc_hi, s83
	s_cselect_b32 s100, s16, s81
	s_cselect_b32 s101, s17, s82
	s_add_u32 s100, s100, 0x80
	s_addc_u32 s101, s101, 0
	global_load_lds_dwordx4 v198, s[100:101]
	s_add_i32 m0, s19, 0x2000
	s_nop 0
	global_load_lds_dwordx4 v128, s[100:101]
	s_setprio 1
	s_barrier
	s_waitcnt lgkmcnt(0)
	v_mfma_f32_16x16x32_bf16 v[88:91], v[194:197], v[162:165], v[88:91]
	v_mfma_f32_16x16x32_bf16 v[96:99], v[204:207], v[162:165], v[96:99]
	v_mfma_f32_16x16x32_bf16 v[80:83], v[194:197], v[170:173], v[80:83]
	v_mfma_f32_16x16x32_bf16 v[84:87], v[204:207], v[170:173], v[84:87]
	v_mfma_f32_16x16x32_bf16 v[72:75], v[194:197], v[178:181], v[72:75]
	v_mfma_f32_16x16x32_bf16 v[76:79], v[204:207], v[178:181], v[76:79]
	v_mfma_f32_16x16x32_bf16 v[56:59], v[194:197], v[186:189], v[56:59]
	v_mfma_f32_16x16x32_bf16 v[64:67], v[204:207], v[186:189], v[64:67]
	v_mfma_f32_16x16x32_bf16 v[88:91], v[200:203], v[166:169], v[88:91]
	v_mfma_f32_16x16x32_bf16 v[96:99], v[208:211], v[166:169], v[96:99]
	v_mfma_f32_16x16x32_bf16 v[80:83], v[200:203], v[174:177], v[80:83]
	v_mfma_f32_16x16x32_bf16 v[84:87], v[208:211], v[174:177], v[84:87]
	v_mfma_f32_16x16x32_bf16 v[72:75], v[200:203], v[182:185], v[72:75]
	v_mfma_f32_16x16x32_bf16 v[76:79], v[208:211], v[182:185], v[76:79]
	v_mfma_f32_16x16x32_bf16 v[56:59], v[200:203], v[190:193], v[56:59]
	v_mfma_f32_16x16x32_bf16 v[64:67], v[208:211], v[190:193], v[64:67]
	s_barrier
	s_setprio 0
	s_mov_b32 m0, s55
	ds_read_b128 v[162:165], v148 offset:49152
	ds_read_b128 v[166:169], v148 offset:50176
	ds_read_b128 v[170:173], v148 offset:51200
	ds_read_b128 v[174:177], v148 offset:52224
	ds_read_b128 v[178:181], v148 offset:53248
	ds_read_b128 v[182:185], v148 offset:54272
	ds_read_b128 v[186:189], v148 offset:55296
	ds_read_b128 v[190:193], v148 offset:56320
	s_add_u32 s100, s20, 0x80
	s_addc_u32 s101, s21, 0
	s_add_i32 vcc_hi, s60, 2
	s_cmp_eq_u32 vcc_hi, s83
	s_cselect_b32 s100, s8, s100
	s_cselect_b32 s101, s9, s101
	s_add_u32 s100, s100, 0x80
	s_addc_u32 s101, s101, 0
	global_load_lds_dwordx4 v132, s[100:101]
	s_mov_b32 m0, s56
	s_nop 0
	global_load_lds_dwordx4 v130, s[100:101]
	s_setprio 1
	s_barrier
	s_waitcnt lgkmcnt(0)
	v_mfma_f32_16x16x32_bf16 v[60:63], v[138:141], v[162:165], v[60:63]
	v_mfma_f32_16x16x32_bf16 v[68:71], v[154:157], v[162:165], v[68:71]
	v_mfma_f32_16x16x32_bf16 v[48:51], v[138:141], v[170:173], v[48:51]
	v_mfma_f32_16x16x32_bf16 v[52:55], v[154:157], v[170:173], v[52:55]
	v_mfma_f32_16x16x32_bf16 v[40:43], v[138:141], v[178:181], v[40:43]
	v_mfma_f32_16x16x32_bf16 v[44:47], v[154:157], v[178:181], v[44:47]
	v_mfma_f32_16x16x32_bf16 v[32:35], v[138:141], v[186:189], v[32:35]
	v_mfma_f32_16x16x32_bf16 v[36:39], v[154:157], v[186:189], v[36:39]
	v_mfma_f32_16x16x32_bf16 v[60:63], v[150:153], v[166:169], v[60:63]
	v_mfma_f32_16x16x32_bf16 v[68:71], v[158:161], v[166:169], v[68:71]
	v_mfma_f32_16x16x32_bf16 v[48:51], v[150:153], v[174:177], v[48:51]
	v_mfma_f32_16x16x32_bf16 v[52:55], v[158:161], v[174:177], v[52:55]
	v_mfma_f32_16x16x32_bf16 v[40:43], v[150:153], v[182:185], v[40:43]
	v_mfma_f32_16x16x32_bf16 v[44:47], v[158:161], v[182:185], v[44:47]
	v_mfma_f32_16x16x32_bf16 v[32:35], v[150:153], v[190:193], v[32:35]
	v_mfma_f32_16x16x32_bf16 v[36:39], v[158:161], v[190:193], v[36:39]
	s_barrier
	s_setprio 0
	s_add_i32 s18, s18, s4
	s_add_i32 vcc_hi, s60, 2
	s_cmp_eq_u32 vcc_hi, s83
	s_cselect_b32 s100, s16, s81
	s_cselect_b32 s101, s17, s82
	s_add_u32 s100, s100, s84
	s_addc_u32 s101, s101, 0
	s_add_u32 s100, s100, 0x80
	s_addc_u32 s101, s101, 0
	s_mov_b32 m0, s18
	s_nop 0
	global_load_lds_dwordx4 v198, s[100:101]
	s_add_i32 m0, s18, 0x2000
	s_nop 0
	global_load_lds_dwordx4 v128, s[100:101]
	s_add_u32 s20, s20, 0x100
	s_addc_u32 s21, s21, 0
	s_add_u32 s81, s81, 0x100
	s_addc_u32 s82, s82, 0
	s_mov_b32 s18, s83
	s_cmp_ge_u32 s83, s57
	s_waitcnt vmcnt(6)
	s_setprio 1
	s_barrier
	v_mfma_f32_16x16x32_bf16 v[120:123], v[194:197], v[162:165], v[120:123]
	v_mfma_f32_16x16x32_bf16 v[124:127], v[204:207], v[162:165], v[124:127]
	v_mfma_f32_16x16x32_bf16 v[112:115], v[194:197], v[170:173], v[112:115]
	v_mfma_f32_16x16x32_bf16 v[116:119], v[204:207], v[170:173], v[116:119]
	v_mfma_f32_16x16x32_bf16 v[104:107], v[194:197], v[178:181], v[104:107]
	v_mfma_f32_16x16x32_bf16 v[108:111], v[204:207], v[178:181], v[108:111]
	v_mfma_f32_16x16x32_bf16 v[92:95], v[194:197], v[186:189], v[92:95]
	v_mfma_f32_16x16x32_bf16 v[100:103], v[204:207], v[186:189], v[100:103]
	v_mfma_f32_16x16x32_bf16 v[120:123], v[200:203], v[166:169], v[120:123]
	v_mfma_f32_16x16x32_bf16 v[124:127], v[208:211], v[166:169], v[124:127]
	v_mfma_f32_16x16x32_bf16 v[112:115], v[200:203], v[174:177], v[112:115]
	v_mfma_f32_16x16x32_bf16 v[116:119], v[208:211], v[174:177], v[116:119]
	v_mfma_f32_16x16x32_bf16 v[104:107], v[200:203], v[182:185], v[104:107]
	v_mfma_f32_16x16x32_bf16 v[108:111], v[208:211], v[182:185], v[108:111]
	v_mfma_f32_16x16x32_bf16 v[92:95], v[200:203], v[190:193], v[92:95]
	v_mfma_f32_16x16x32_bf16 v[100:103], v[208:211], v[190:193], v[100:103]
	s_barrier
	s_setprio 0
	s_cbranch_scc0 .LBB0_743
